# GEMM1 dilated-query epilogue rewritten by hand: rotary table rows loaded up front with one wait, SGPR row base + per-lane offset for the P0 stores, no store drains
# speedup vs baseline: 1.0092x; 1.0092x over previous
.LBB0_486:
	s_andn2_b64 vcc, exec, s[4:5]
	s_cbranch_vccnz .LBB0_544
	s_cmp_lg_u32 s59, 0
	s_cbranch_scc1 .Lepi4_plain
	s_lshl_b32 s8, s90, 8
	s_add_i32 s8, s8, s57
	v_mul_u32_u24_e32 v168, 0x5800, v184
	v_lshl_add_u32 v168, v185, 4, v168
	s_mul_i32 s20, s8, 0x5800
	s_lshl_b32 s6, s82, 9
	s_add_u32 s20, s20, s6
	s_lshl_b32 s6, s59, 1
	s_add_u32 s20, s20, s6
	s_add_u32 s4, s0, s20
	s_addc_u32 s5, s1, 0
	v_add_u32_e32 v169, s8, v184
	v_lshlrev_b32_e32 v169, 6, v169
	v_lshl_add_u32 v169, v185, 4, v169
	v_add_u32_e32 v170, 0x2000, v169
	global_load_dwordx4 v[190:193], v169, s[16:17]
	global_load_dwordx4 v[226:229], v169, s[18:19]
	global_load_dwordx4 v[194:197], v169, s[16:17] offset:1024
	global_load_dwordx4 v[230:233], v169, s[18:19] offset:1024
	global_load_dwordx4 v[198:201], v169, s[16:17] offset:2048
	global_load_dwordx4 v[234:237], v169, s[18:19] offset:2048
	global_load_dwordx4 v[202:205], v169, s[16:17] offset:3072
	global_load_dwordx4 v[238:241], v169, s[18:19] offset:3072
	global_load_dwordx4 v[210:213], v170, s[16:17]
	global_load_dwordx4 v[242:245], v170, s[18:19]
	global_load_dwordx4 v[214:217], v170, s[16:17] offset:1024
	global_load_dwordx4 v[246:249], v170, s[18:19] offset:1024
	global_load_dwordx4 v[218:221], v170, s[16:17] offset:2048
	global_load_dwordx4 v[140:143], v170, s[18:19] offset:2048
	global_load_dwordx4 v[222:225], v170, s[16:17] offset:3072
	global_load_dwordx4 v[144:147], v170, s[18:19] offset:3072
	s_waitcnt vmcnt(0)
	s_nop 1
	v_mul_f32_e32 v171, v125, v226
	v_fma_f32 v132, v124, v190, -v171
	v_mul_f32_e32 v171, v124, v226
	v_fma_f32 v136, v125, v190, v171
	v_mul_f32_e32 v171, v127, v227
	v_fma_f32 v133, v126, v191, -v171
	v_mul_f32_e32 v171, v126, v227
	v_fma_f32 v137, v127, v191, v171
	v_mul_f32_e32 v171, v121, v228
	v_fma_f32 v134, v120, v192, -v171
	v_mul_f32_e32 v171, v120, v228
	v_fma_f32 v138, v121, v192, v171
	v_mul_f32_e32 v171, v123, v229
	v_fma_f32 v135, v122, v193, -v171
	v_mul_f32_e32 v171, v122, v229
	v_fma_f32 v139, v123, v193, v171
	v_mul_f32_e32 v132, s30, v132
	v_mul_f32_e32 v136, s30, v136
	v_mul_f32_e32 v133, s30, v133
	v_mul_f32_e32 v137, s30, v137
	v_mul_f32_e32 v134, s30, v134
	v_mul_f32_e32 v138, s30, v138
	v_mul_f32_e32 v135, s30, v135
	v_mul_f32_e32 v139, s30, v139
	v_cvt_pk_bf16_f32 v128, v132, v136
	v_cvt_pk_bf16_f32 v129, v133, v137
	v_cvt_pk_bf16_f32 v130, v134, v138
	v_cvt_pk_bf16_f32 v131, v135, v139
	global_store_dwordx4 v168, v[128:131], s[4:5]
	s_nop 1
	v_mul_f32_e32 v171, v117, v226
	v_fma_f32 v132, v116, v190, -v171
	v_mul_f32_e32 v171, v116, v226
	v_fma_f32 v136, v117, v190, v171
	v_mul_f32_e32 v171, v119, v227
	v_fma_f32 v133, v118, v191, -v171
	v_mul_f32_e32 v171, v118, v227
	v_fma_f32 v137, v119, v191, v171
	v_mul_f32_e32 v171, v113, v228
	v_fma_f32 v134, v112, v192, -v171
	v_mul_f32_e32 v171, v112, v228
	v_fma_f32 v138, v113, v192, v171
	v_mul_f32_e32 v171, v115, v229
	v_fma_f32 v135, v114, v193, -v171
	v_mul_f32_e32 v171, v114, v229
	v_fma_f32 v139, v115, v193, v171
	v_mul_f32_e32 v132, s30, v132
	v_mul_f32_e32 v136, s30, v136
	v_mul_f32_e32 v133, s30, v133
	v_mul_f32_e32 v137, s30, v137
	v_mul_f32_e32 v134, s30, v134
	v_mul_f32_e32 v138, s30, v138
	v_mul_f32_e32 v135, s30, v135
	v_mul_f32_e32 v139, s30, v139
	v_cvt_pk_bf16_f32 v128, v132, v136
	v_cvt_pk_bf16_f32 v129, v133, v137
	v_cvt_pk_bf16_f32 v130, v134, v138
	v_cvt_pk_bf16_f32 v131, v135, v139
	global_store_dwordx4 v168, v[128:131], s[4:5] offset:256
	s_add_u32 s4, s4, 0x58000
	s_addc_u32 s5, s5, 0
	s_nop 1
	v_mul_f32_e32 v171, v109, v230
	v_fma_f32 v132, v108, v194, -v171
	v_mul_f32_e32 v171, v108, v230
	v_fma_f32 v136, v109, v194, v171
	v_mul_f32_e32 v171, v111, v231
	v_fma_f32 v133, v110, v195, -v171
	v_mul_f32_e32 v171, v110, v231
	v_fma_f32 v137, v111, v195, v171
	v_mul_f32_e32 v171, v105, v232
	v_fma_f32 v134, v104, v196, -v171
	v_mul_f32_e32 v171, v104, v232
	v_fma_f32 v138, v105, v196, v171
	v_mul_f32_e32 v171, v107, v233
	v_fma_f32 v135, v106, v197, -v171
	v_mul_f32_e32 v171, v106, v233
	v_fma_f32 v139, v107, v197, v171
	v_mul_f32_e32 v132, s30, v132
	v_mul_f32_e32 v136, s30, v136
	v_mul_f32_e32 v133, s30, v133
	v_mul_f32_e32 v137, s30, v137
	v_mul_f32_e32 v134, s30, v134
	v_mul_f32_e32 v138, s30, v138
	v_mul_f32_e32 v135, s30, v135
	v_mul_f32_e32 v139, s30, v139
	v_cvt_pk_bf16_f32 v128, v132, v136
	v_cvt_pk_bf16_f32 v129, v133, v137
	v_cvt_pk_bf16_f32 v130, v134, v138
	v_cvt_pk_bf16_f32 v131, v135, v139
	global_store_dwordx4 v168, v[128:131], s[4:5]
	s_nop 1
	v_mul_f32_e32 v171, v101, v230
	v_fma_f32 v132, v100, v194, -v171
	v_mul_f32_e32 v171, v100, v230
	v_fma_f32 v136, v101, v194, v171
	v_mul_f32_e32 v171, v103, v231
	v_fma_f32 v133, v102, v195, -v171
	v_mul_f32_e32 v171, v102, v231
	v_fma_f32 v137, v103, v195, v171
	v_mul_f32_e32 v171, v97, v232
	v_fma_f32 v134, v96, v196, -v171
	v_mul_f32_e32 v171, v96, v232
	v_fma_f32 v138, v97, v196, v171
	v_mul_f32_e32 v171, v99, v233
	v_fma_f32 v135, v98, v197, -v171
	v_mul_f32_e32 v171, v98, v233
	v_fma_f32 v139, v99, v197, v171
	v_mul_f32_e32 v132, s30, v132
	v_mul_f32_e32 v136, s30, v136
	v_mul_f32_e32 v133, s30, v133
	v_mul_f32_e32 v137, s30, v137
	v_mul_f32_e32 v134, s30, v134
	v_mul_f32_e32 v138, s30, v138
	v_mul_f32_e32 v135, s30, v135
	v_mul_f32_e32 v139, s30, v139
	v_cvt_pk_bf16_f32 v128, v132, v136
	v_cvt_pk_bf16_f32 v129, v133, v137
	v_cvt_pk_bf16_f32 v130, v134, v138
	v_cvt_pk_bf16_f32 v131, v135, v139
	global_store_dwordx4 v168, v[128:131], s[4:5] offset:256
	s_add_u32 s4, s4, 0x58000
	s_addc_u32 s5, s5, 0
	s_nop 1
	v_mul_f32_e32 v171, v93, v234
	v_fma_f32 v132, v92, v198, -v171
	v_mul_f32_e32 v171, v92, v234
	v_fma_f32 v136, v93, v198, v171
	v_mul_f32_e32 v171, v95, v235
	v_fma_f32 v133, v94, v199, -v171
	v_mul_f32_e32 v171, v94, v235
	v_fma_f32 v137, v95, v199, v171
	v_mul_f32_e32 v171, v89, v236
	v_fma_f32 v134, v88, v200, -v171
	v_mul_f32_e32 v171, v88, v236
	v_fma_f32 v138, v89, v200, v171
	v_mul_f32_e32 v171, v91, v237
	v_fma_f32 v135, v90, v201, -v171
	v_mul_f32_e32 v171, v90, v237
	v_fma_f32 v139, v91, v201, v171
	v_mul_f32_e32 v132, s30, v132
	v_mul_f32_e32 v136, s30, v136
	v_mul_f32_e32 v133, s30, v133
	v_mul_f32_e32 v137, s30, v137
	v_mul_f32_e32 v134, s30, v134
	v_mul_f32_e32 v138, s30, v138
	v_mul_f32_e32 v135, s30, v135
	v_mul_f32_e32 v139, s30, v139
	v_cvt_pk_bf16_f32 v128, v132, v136
	v_cvt_pk_bf16_f32 v129, v133, v137
	v_cvt_pk_bf16_f32 v130, v134, v138
	v_cvt_pk_bf16_f32 v131, v135, v139
	global_store_dwordx4 v168, v[128:131], s[4:5]
	s_nop 1
	v_mul_f32_e32 v171, v85, v234
	v_fma_f32 v132, v84, v198, -v171
	v_mul_f32_e32 v171, v84, v234
	v_fma_f32 v136, v85, v198, v171
	v_mul_f32_e32 v171, v87, v235
	v_fma_f32 v133, v86, v199, -v171
	v_mul_f32_e32 v171, v86, v235
	v_fma_f32 v137, v87, v199, v171
	v_mul_f32_e32 v171, v81, v236
	v_fma_f32 v134, v80, v200, -v171
	v_mul_f32_e32 v171, v80, v236
	v_fma_f32 v138, v81, v200, v171
	v_mul_f32_e32 v171, v83, v237
	v_fma_f32 v135, v82, v201, -v171
	v_mul_f32_e32 v171, v82, v237
	v_fma_f32 v139, v83, v201, v171
	v_mul_f32_e32 v132, s30, v132
	v_mul_f32_e32 v136, s30, v136
	v_mul_f32_e32 v133, s30, v133
	v_mul_f32_e32 v137, s30, v137
	v_mul_f32_e32 v134, s30, v134
	v_mul_f32_e32 v138, s30, v138
	v_mul_f32_e32 v135, s30, v135
	v_mul_f32_e32 v139, s30, v139
	v_cvt_pk_bf16_f32 v128, v132, v136
	v_cvt_pk_bf16_f32 v129, v133, v137
	v_cvt_pk_bf16_f32 v130, v134, v138
	v_cvt_pk_bf16_f32 v131, v135, v139
	global_store_dwordx4 v168, v[128:131], s[4:5] offset:256
	s_add_u32 s4, s4, 0x58000
	s_addc_u32 s5, s5, 0
	s_nop 1
	v_mul_f32_e32 v171, v77, v238
	v_fma_f32 v132, v76, v202, -v171
	v_mul_f32_e32 v171, v76, v238
	v_fma_f32 v136, v77, v202, v171
	v_mul_f32_e32 v171, v79, v239
	v_fma_f32 v133, v78, v203, -v171
	v_mul_f32_e32 v171, v78, v239
	v_fma_f32 v137, v79, v203, v171
	v_mul_f32_e32 v171, v73, v240
	v_fma_f32 v134, v72, v204, -v171
	v_mul_f32_e32 v171, v72, v240
	v_fma_f32 v138, v73, v204, v171
	v_mul_f32_e32 v171, v75, v241
	v_fma_f32 v135, v74, v205, -v171
	v_mul_f32_e32 v171, v74, v241
	v_fma_f32 v139, v75, v205, v171
	v_mul_f32_e32 v132, s30, v132
	v_mul_f32_e32 v136, s30, v136
	v_mul_f32_e32 v133, s30, v133
	v_mul_f32_e32 v137, s30, v137
	v_mul_f32_e32 v134, s30, v134
	v_mul_f32_e32 v138, s30, v138
	v_mul_f32_e32 v135, s30, v135
	v_mul_f32_e32 v139, s30, v139
	v_cvt_pk_bf16_f32 v128, v132, v136
	v_cvt_pk_bf16_f32 v129, v133, v137
	v_cvt_pk_bf16_f32 v130, v134, v138
	v_cvt_pk_bf16_f32 v131, v135, v139
	global_store_dwordx4 v168, v[128:131], s[4:5]
	s_nop 1
	v_mul_f32_e32 v171, v69, v238
	v_fma_f32 v132, v68, v202, -v171
	v_mul_f32_e32 v171, v68, v238
	v_fma_f32 v136, v69, v202, v171
	v_mul_f32_e32 v171, v71, v239
	v_fma_f32 v133, v70, v203, -v171
	v_mul_f32_e32 v171, v70, v239
	v_fma_f32 v137, v71, v203, v171
	v_mul_f32_e32 v171, v65, v240
	v_fma_f32 v134, v64, v204, -v171
	v_mul_f32_e32 v171, v64, v240
	v_fma_f32 v138, v65, v204, v171
	v_mul_f32_e32 v171, v67, v241
	v_fma_f32 v135, v66, v205, -v171
	v_mul_f32_e32 v171, v66, v241
	v_fma_f32 v139, v67, v205, v171
	v_mul_f32_e32 v132, s30, v132
	v_mul_f32_e32 v136, s30, v136
	v_mul_f32_e32 v133, s30, v133
	v_mul_f32_e32 v137, s30, v137
	v_mul_f32_e32 v134, s30, v134
	v_mul_f32_e32 v138, s30, v138
	v_mul_f32_e32 v135, s30, v135
	v_mul_f32_e32 v139, s30, v139
	v_cvt_pk_bf16_f32 v128, v132, v136
	v_cvt_pk_bf16_f32 v129, v133, v137
	v_cvt_pk_bf16_f32 v130, v134, v138
	v_cvt_pk_bf16_f32 v131, v135, v139
	global_store_dwordx4 v168, v[128:131], s[4:5] offset:256
	s_add_u32 s4, s4, 0x1b8000
	s_addc_u32 s5, s5, 0
	s_nop 1
	v_mul_f32_e32 v171, v61, v242
	v_fma_f32 v132, v60, v210, -v171
	v_mul_f32_e32 v171, v60, v242
	v_fma_f32 v136, v61, v210, v171
	v_mul_f32_e32 v171, v63, v243
	v_fma_f32 v133, v62, v211, -v171
	v_mul_f32_e32 v171, v62, v243
	v_fma_f32 v137, v63, v211, v171
	v_mul_f32_e32 v171, v57, v244
	v_fma_f32 v134, v56, v212, -v171
	v_mul_f32_e32 v171, v56, v244
	v_fma_f32 v138, v57, v212, v171
	v_mul_f32_e32 v171, v59, v245
	v_fma_f32 v135, v58, v213, -v171
	v_mul_f32_e32 v171, v58, v245
	v_fma_f32 v139, v59, v213, v171
	v_mul_f32_e32 v132, s30, v132
	v_mul_f32_e32 v136, s30, v136
	v_mul_f32_e32 v133, s30, v133
	v_mul_f32_e32 v137, s30, v137
	v_mul_f32_e32 v134, s30, v134
	v_mul_f32_e32 v138, s30, v138
	v_mul_f32_e32 v135, s30, v135
	v_mul_f32_e32 v139, s30, v139
	v_cvt_pk_bf16_f32 v128, v132, v136
	v_cvt_pk_bf16_f32 v129, v133, v137
	v_cvt_pk_bf16_f32 v130, v134, v138
	v_cvt_pk_bf16_f32 v131, v135, v139
	global_store_dwordx4 v168, v[128:131], s[4:5]
	s_nop 1
	v_mul_f32_e32 v171, v53, v242
	v_fma_f32 v132, v52, v210, -v171
	v_mul_f32_e32 v171, v52, v242
	v_fma_f32 v136, v53, v210, v171
	v_mul_f32_e32 v171, v55, v243
	v_fma_f32 v133, v54, v211, -v171
	v_mul_f32_e32 v171, v54, v243
	v_fma_f32 v137, v55, v211, v171
	v_mul_f32_e32 v171, v49, v244
	v_fma_f32 v134, v48, v212, -v171
	v_mul_f32_e32 v171, v48, v244
	v_fma_f32 v138, v49, v212, v171
	v_mul_f32_e32 v171, v51, v245
	v_fma_f32 v135, v50, v213, -v171
	v_mul_f32_e32 v171, v50, v245
	v_fma_f32 v139, v51, v213, v171
	v_mul_f32_e32 v132, s30, v132
	v_mul_f32_e32 v136, s30, v136
	v_mul_f32_e32 v133, s30, v133
	v_mul_f32_e32 v137, s30, v137
	v_mul_f32_e32 v134, s30, v134
	v_mul_f32_e32 v138, s30, v138
	v_mul_f32_e32 v135, s30, v135
	v_mul_f32_e32 v139, s30, v139
	v_cvt_pk_bf16_f32 v128, v132, v136
	v_cvt_pk_bf16_f32 v129, v133, v137
	v_cvt_pk_bf16_f32 v130, v134, v138
	v_cvt_pk_bf16_f32 v131, v135, v139
	global_store_dwordx4 v168, v[128:131], s[4:5] offset:256
	s_add_u32 s4, s4, 0x58000
	s_addc_u32 s5, s5, 0
	s_nop 1
	v_mul_f32_e32 v171, v45, v246
	v_fma_f32 v132, v44, v214, -v171
	v_mul_f32_e32 v171, v44, v246
	v_fma_f32 v136, v45, v214, v171
	v_mul_f32_e32 v171, v47, v247
	v_fma_f32 v133, v46, v215, -v171
	v_mul_f32_e32 v171, v46, v247
	v_fma_f32 v137, v47, v215, v171
	v_mul_f32_e32 v171, v41, v248
	v_fma_f32 v134, v40, v216, -v171
	v_mul_f32_e32 v171, v40, v248
	v_fma_f32 v138, v41, v216, v171
	v_mul_f32_e32 v171, v43, v249
	v_fma_f32 v135, v42, v217, -v171
	v_mul_f32_e32 v171, v42, v249
	v_fma_f32 v139, v43, v217, v171
	v_mul_f32_e32 v132, s30, v132
	v_mul_f32_e32 v136, s30, v136
	v_mul_f32_e32 v133, s30, v133
	v_mul_f32_e32 v137, s30, v137
	v_mul_f32_e32 v134, s30, v134
	v_mul_f32_e32 v138, s30, v138
	v_mul_f32_e32 v135, s30, v135
	v_mul_f32_e32 v139, s30, v139
	v_cvt_pk_bf16_f32 v128, v132, v136
	v_cvt_pk_bf16_f32 v129, v133, v137
	v_cvt_pk_bf16_f32 v130, v134, v138
	v_cvt_pk_bf16_f32 v131, v135, v139
	global_store_dwordx4 v168, v[128:131], s[4:5]
	s_nop 1
	v_mul_f32_e32 v171, v37, v246
	v_fma_f32 v132, v36, v214, -v171
	v_mul_f32_e32 v171, v36, v246
	v_fma_f32 v136, v37, v214, v171
	v_mul_f32_e32 v171, v39, v247
	v_fma_f32 v133, v38, v215, -v171
	v_mul_f32_e32 v171, v38, v247
	v_fma_f32 v137, v39, v215, v171
	v_mul_f32_e32 v171, v33, v248
	v_fma_f32 v134, v32, v216, -v171
	v_mul_f32_e32 v171, v32, v248
	v_fma_f32 v138, v33, v216, v171
	v_mul_f32_e32 v171, v35, v249
	v_fma_f32 v135, v34, v217, -v171
	v_mul_f32_e32 v171, v34, v249
	v_fma_f32 v139, v35, v217, v171
	v_mul_f32_e32 v132, s30, v132
	v_mul_f32_e32 v136, s30, v136
	v_mul_f32_e32 v133, s30, v133
	v_mul_f32_e32 v137, s30, v137
	v_mul_f32_e32 v134, s30, v134
	v_mul_f32_e32 v138, s30, v138
	v_mul_f32_e32 v135, s30, v135
	v_mul_f32_e32 v139, s30, v139
	v_cvt_pk_bf16_f32 v128, v132, v136
	v_cvt_pk_bf16_f32 v129, v133, v137
	v_cvt_pk_bf16_f32 v130, v134, v138
	v_cvt_pk_bf16_f32 v131, v135, v139
	global_store_dwordx4 v168, v[128:131], s[4:5] offset:256
	s_add_u32 s4, s4, 0x58000
	s_addc_u32 s5, s5, 0
	s_nop 1
	v_mul_f32_e32 v171, v29, v140
	v_fma_f32 v132, v28, v218, -v171
	v_mul_f32_e32 v171, v28, v140
	v_fma_f32 v136, v29, v218, v171
	v_mul_f32_e32 v171, v31, v141
	v_fma_f32 v133, v30, v219, -v171
	v_mul_f32_e32 v171, v30, v141
	v_fma_f32 v137, v31, v219, v171
	v_mul_f32_e32 v171, v25, v142
	v_fma_f32 v134, v24, v220, -v171
	v_mul_f32_e32 v171, v24, v142
	v_fma_f32 v138, v25, v220, v171
	v_mul_f32_e32 v171, v27, v143
	v_fma_f32 v135, v26, v221, -v171
	v_mul_f32_e32 v171, v26, v143
	v_fma_f32 v139, v27, v221, v171
	v_mul_f32_e32 v132, s30, v132
	v_mul_f32_e32 v136, s30, v136
	v_mul_f32_e32 v133, s30, v133
	v_mul_f32_e32 v137, s30, v137
	v_mul_f32_e32 v134, s30, v134
	v_mul_f32_e32 v138, s30, v138
	v_mul_f32_e32 v135, s30, v135
	v_mul_f32_e32 v139, s30, v139
	v_cvt_pk_bf16_f32 v128, v132, v136
	v_cvt_pk_bf16_f32 v129, v133, v137
	v_cvt_pk_bf16_f32 v130, v134, v138
	v_cvt_pk_bf16_f32 v131, v135, v139
	global_store_dwordx4 v168, v[128:131], s[4:5]
	s_nop 1
	v_mul_f32_e32 v171, v21, v140
	v_fma_f32 v132, v20, v218, -v171
	v_mul_f32_e32 v171, v20, v140
	v_fma_f32 v136, v21, v218, v171
	v_mul_f32_e32 v171, v23, v141
	v_fma_f32 v133, v22, v219, -v171
	v_mul_f32_e32 v171, v22, v141
	v_fma_f32 v137, v23, v219, v171
	v_mul_f32_e32 v171, v17, v142
	v_fma_f32 v134, v16, v220, -v171
	v_mul_f32_e32 v171, v16, v142
	v_fma_f32 v138, v17, v220, v171
	v_mul_f32_e32 v171, v19, v143
	v_fma_f32 v135, v18, v221, -v171
	v_mul_f32_e32 v171, v18, v143
	v_fma_f32 v139, v19, v221, v171
	v_mul_f32_e32 v132, s30, v132
	v_mul_f32_e32 v136, s30, v136
	v_mul_f32_e32 v133, s30, v133
	v_mul_f32_e32 v137, s30, v137
	v_mul_f32_e32 v134, s30, v134
	v_mul_f32_e32 v138, s30, v138
	v_mul_f32_e32 v135, s30, v135
	v_mul_f32_e32 v139, s30, v139
	v_cvt_pk_bf16_f32 v128, v132, v136
	v_cvt_pk_bf16_f32 v129, v133, v137
	v_cvt_pk_bf16_f32 v130, v134, v138
	v_cvt_pk_bf16_f32 v131, v135, v139
	global_store_dwordx4 v168, v[128:131], s[4:5] offset:256
	s_add_u32 s4, s4, 0x58000
	s_addc_u32 s5, s5, 0
	s_nop 1
	v_mul_f32_e32 v171, v13, v144
	v_fma_f32 v132, v12, v222, -v171
	v_mul_f32_e32 v171, v12, v144
	v_fma_f32 v136, v13, v222, v171
	v_mul_f32_e32 v171, v15, v145
	v_fma_f32 v133, v14, v223, -v171
	v_mul_f32_e32 v171, v14, v145
	v_fma_f32 v137, v15, v223, v171
	v_mul_f32_e32 v171, v9, v146
	v_fma_f32 v134, v8, v224, -v171
	v_mul_f32_e32 v171, v8, v146
	v_fma_f32 v138, v9, v224, v171
	v_mul_f32_e32 v171, v11, v147
	v_fma_f32 v135, v10, v225, -v171
	v_mul_f32_e32 v171, v10, v147
	v_fma_f32 v139, v11, v225, v171
	v_mul_f32_e32 v132, s30, v132
	v_mul_f32_e32 v136, s30, v136
	v_mul_f32_e32 v133, s30, v133
	v_mul_f32_e32 v137, s30, v137
	v_mul_f32_e32 v134, s30, v134
	v_mul_f32_e32 v138, s30, v138
	v_mul_f32_e32 v135, s30, v135
	v_mul_f32_e32 v139, s30, v139
	v_cvt_pk_bf16_f32 v128, v132, v136
	v_cvt_pk_bf16_f32 v129, v133, v137
	v_cvt_pk_bf16_f32 v130, v134, v138
	v_cvt_pk_bf16_f32 v131, v135, v139
	global_store_dwordx4 v168, v[128:131], s[4:5]
	s_nop 1
	v_mul_f32_e32 v171, v5, v144
	v_fma_f32 v132, v4, v222, -v171
	v_mul_f32_e32 v171, v4, v144
	v_fma_f32 v136, v5, v222, v171
	v_mul_f32_e32 v171, v7, v145
	v_fma_f32 v133, v6, v223, -v171
	v_mul_f32_e32 v171, v6, v145
	v_fma_f32 v137, v7, v223, v171
	v_mul_f32_e32 v171, v1, v146
	v_fma_f32 v134, v0, v224, -v171
	v_mul_f32_e32 v171, v0, v146
	v_fma_f32 v138, v1, v224, v171
	v_mul_f32_e32 v171, v3, v147
	v_fma_f32 v135, v2, v225, -v171
	v_mul_f32_e32 v171, v2, v147
	v_fma_f32 v139, v3, v225, v171
	v_mul_f32_e32 v132, s30, v132
	v_mul_f32_e32 v136, s30, v136
	v_mul_f32_e32 v133, s30, v133
	v_mul_f32_e32 v137, s30, v137
	v_mul_f32_e32 v134, s30, v134
	v_mul_f32_e32 v138, s30, v138
	v_mul_f32_e32 v135, s30, v135
	v_mul_f32_e32 v139, s30, v139
	v_cvt_pk_bf16_f32 v128, v132, v136
	v_cvt_pk_bf16_f32 v129, v133, v137
	v_cvt_pk_bf16_f32 v130, v134, v138
	v_cvt_pk_bf16_f32 v131, v135, v139
	global_store_dwordx4 v168, v[128:131], s[4:5] offset:256
	s_branch .Lepi4_done
.Lepi4_plain:
	s_lshl_b32 s8, s90, 8
	s_add_i32 s8, s8, s57
	v_mul_u32_u24_e32 v168, 0x5800, v184
	v_lshl_add_u32 v168, v185, 4, v168
	s_mul_i32 s20, s8, 0x5800
	s_lshl_b32 s6, s82, 9
	s_add_u32 s20, s20, s6
	s_lshl_b32 s6, s59, 1
	s_add_u32 s20, s20, s6
	s_add_u32 s4, s0, s20
	s_addc_u32 s5, s1, 0
	s_nop 1
	v_mul_f32_e32 v132, s30, v124
	v_mul_f32_e32 v136, s30, v125
	v_mul_f32_e32 v133, s30, v126
	v_mul_f32_e32 v137, s30, v127
	v_mul_f32_e32 v134, s30, v120
	v_mul_f32_e32 v138, s30, v121
	v_mul_f32_e32 v135, s30, v122
	v_mul_f32_e32 v139, s30, v123
	v_cvt_pk_bf16_f32 v128, v132, v136
	v_cvt_pk_bf16_f32 v129, v133, v137
	v_cvt_pk_bf16_f32 v130, v134, v138
	v_cvt_pk_bf16_f32 v131, v135, v139
	global_store_dwordx4 v168, v[128:131], s[4:5]
	s_nop 1
	v_mul_f32_e32 v132, s30, v116
	v_mul_f32_e32 v136, s30, v117
	v_mul_f32_e32 v133, s30, v118
	v_mul_f32_e32 v137, s30, v119
	v_mul_f32_e32 v134, s30, v112
	v_mul_f32_e32 v138, s30, v113
	v_mul_f32_e32 v135, s30, v114
	v_mul_f32_e32 v139, s30, v115
	v_cvt_pk_bf16_f32 v128, v132, v136
	v_cvt_pk_bf16_f32 v129, v133, v137
	v_cvt_pk_bf16_f32 v130, v134, v138
	v_cvt_pk_bf16_f32 v131, v135, v139
	global_store_dwordx4 v168, v[128:131], s[4:5] offset:256
	s_add_u32 s4, s4, 0x58000
	s_addc_u32 s5, s5, 0
	s_nop 1
	v_mul_f32_e32 v132, s30, v108
	v_mul_f32_e32 v136, s30, v109
	v_mul_f32_e32 v133, s30, v110
	v_mul_f32_e32 v137, s30, v111
	v_mul_f32_e32 v134, s30, v104
	v_mul_f32_e32 v138, s30, v105
	v_mul_f32_e32 v135, s30, v106
	v_mul_f32_e32 v139, s30, v107
	v_cvt_pk_bf16_f32 v128, v132, v136
	v_cvt_pk_bf16_f32 v129, v133, v137
	v_cvt_pk_bf16_f32 v130, v134, v138
	v_cvt_pk_bf16_f32 v131, v135, v139
	global_store_dwordx4 v168, v[128:131], s[4:5]
	s_nop 1
	v_mul_f32_e32 v132, s30, v100
	v_mul_f32_e32 v136, s30, v101
	v_mul_f32_e32 v133, s30, v102
	v_mul_f32_e32 v137, s30, v103
	v_mul_f32_e32 v134, s30, v96
	v_mul_f32_e32 v138, s30, v97
	v_mul_f32_e32 v135, s30, v98
	v_mul_f32_e32 v139, s30, v99
	v_cvt_pk_bf16_f32 v128, v132, v136
	v_cvt_pk_bf16_f32 v129, v133, v137
	v_cvt_pk_bf16_f32 v130, v134, v138
	v_cvt_pk_bf16_f32 v131, v135, v139
	global_store_dwordx4 v168, v[128:131], s[4:5] offset:256
	s_add_u32 s4, s4, 0x58000
	s_addc_u32 s5, s5, 0
	s_nop 1
	v_mul_f32_e32 v132, s30, v92
	v_mul_f32_e32 v136, s30, v93
	v_mul_f32_e32 v133, s30, v94
	v_mul_f32_e32 v137, s30, v95
	v_mul_f32_e32 v134, s30, v88
	v_mul_f32_e32 v138, s30, v89
	v_mul_f32_e32 v135, s30, v90
	v_mul_f32_e32 v139, s30, v91
	v_cvt_pk_bf16_f32 v128, v132, v136
	v_cvt_pk_bf16_f32 v129, v133, v137
	v_cvt_pk_bf16_f32 v130, v134, v138
	v_cvt_pk_bf16_f32 v131, v135, v139
	global_store_dwordx4 v168, v[128:131], s[4:5]
	s_nop 1
	v_mul_f32_e32 v132, s30, v84
	v_mul_f32_e32 v136, s30, v85
	v_mul_f32_e32 v133, s30, v86
	v_mul_f32_e32 v137, s30, v87
	v_mul_f32_e32 v134, s30, v80
	v_mul_f32_e32 v138, s30, v81
	v_mul_f32_e32 v135, s30, v82
	v_mul_f32_e32 v139, s30, v83
	v_cvt_pk_bf16_f32 v128, v132, v136
	v_cvt_pk_bf16_f32 v129, v133, v137
	v_cvt_pk_bf16_f32 v130, v134, v138
	v_cvt_pk_bf16_f32 v131, v135, v139
	global_store_dwordx4 v168, v[128:131], s[4:5] offset:256
	s_add_u32 s4, s4, 0x58000
	s_addc_u32 s5, s5, 0
	s_nop 1
	v_mul_f32_e32 v132, s30, v76
	v_mul_f32_e32 v136, s30, v77
	v_mul_f32_e32 v133, s30, v78
	v_mul_f32_e32 v137, s30, v79
	v_mul_f32_e32 v134, s30, v72
	v_mul_f32_e32 v138, s30, v73
	v_mul_f32_e32 v135, s30, v74
	v_mul_f32_e32 v139, s30, v75
	v_cvt_pk_bf16_f32 v128, v132, v136
	v_cvt_pk_bf16_f32 v129, v133, v137
	v_cvt_pk_bf16_f32 v130, v134, v138
	v_cvt_pk_bf16_f32 v131, v135, v139
	global_store_dwordx4 v168, v[128:131], s[4:5]
	s_nop 1
	v_mul_f32_e32 v132, s30, v68
	v_mul_f32_e32 v136, s30, v69
	v_mul_f32_e32 v133, s30, v70
	v_mul_f32_e32 v137, s30, v71
	v_mul_f32_e32 v134, s30, v64
	v_mul_f32_e32 v138, s30, v65
	v_mul_f32_e32 v135, s30, v66
	v_mul_f32_e32 v139, s30, v67
	v_cvt_pk_bf16_f32 v128, v132, v136
	v_cvt_pk_bf16_f32 v129, v133, v137
	v_cvt_pk_bf16_f32 v130, v134, v138
	v_cvt_pk_bf16_f32 v131, v135, v139
	global_store_dwordx4 v168, v[128:131], s[4:5] offset:256
	s_add_u32 s4, s4, 0x1b8000
	s_addc_u32 s5, s5, 0
	s_nop 1
	v_mul_f32_e32 v132, s30, v60
	v_mul_f32_e32 v136, s30, v61
	v_mul_f32_e32 v133, s30, v62
	v_mul_f32_e32 v137, s30, v63
	v_mul_f32_e32 v134, s30, v56
	v_mul_f32_e32 v138, s30, v57
	v_mul_f32_e32 v135, s30, v58
	v_mul_f32_e32 v139, s30, v59
	v_cvt_pk_bf16_f32 v128, v132, v136
	v_cvt_pk_bf16_f32 v129, v133, v137
	v_cvt_pk_bf16_f32 v130, v134, v138
	v_cvt_pk_bf16_f32 v131, v135, v139
	global_store_dwordx4 v168, v[128:131], s[4:5]
	s_nop 1
	v_mul_f32_e32 v132, s30, v52
	v_mul_f32_e32 v136, s30, v53
	v_mul_f32_e32 v133, s30, v54
	v_mul_f32_e32 v137, s30, v55
	v_mul_f32_e32 v134, s30, v48
	v_mul_f32_e32 v138, s30, v49
	v_mul_f32_e32 v135, s30, v50
	v_mul_f32_e32 v139, s30, v51
	v_cvt_pk_bf16_f32 v128, v132, v136
	v_cvt_pk_bf16_f32 v129, v133, v137
	v_cvt_pk_bf16_f32 v130, v134, v138
	v_cvt_pk_bf16_f32 v131, v135, v139
	global_store_dwordx4 v168, v[128:131], s[4:5] offset:256
	s_add_u32 s4, s4, 0x58000
	s_addc_u32 s5, s5, 0
	s_nop 1
	v_mul_f32_e32 v132, s30, v44
	v_mul_f32_e32 v136, s30, v45
	v_mul_f32_e32 v133, s30, v46
	v_mul_f32_e32 v137, s30, v47
	v_mul_f32_e32 v134, s30, v40
	v_mul_f32_e32 v138, s30, v41
	v_mul_f32_e32 v135, s30, v42
	v_mul_f32_e32 v139, s30, v43
	v_cvt_pk_bf16_f32 v128, v132, v136
	v_cvt_pk_bf16_f32 v129, v133, v137
	v_cvt_pk_bf16_f32 v130, v134, v138
	v_cvt_pk_bf16_f32 v131, v135, v139
	global_store_dwordx4 v168, v[128:131], s[4:5]
	s_nop 1
	v_mul_f32_e32 v132, s30, v36
	v_mul_f32_e32 v136, s30, v37
	v_mul_f32_e32 v133, s30, v38
	v_mul_f32_e32 v137, s30, v39
	v_mul_f32_e32 v134, s30, v32
	v_mul_f32_e32 v138, s30, v33
	v_mul_f32_e32 v135, s30, v34
	v_mul_f32_e32 v139, s30, v35
	v_cvt_pk_bf16_f32 v128, v132, v136
	v_cvt_pk_bf16_f32 v129, v133, v137
	v_cvt_pk_bf16_f32 v130, v134, v138
	v_cvt_pk_bf16_f32 v131, v135, v139
	global_store_dwordx4 v168, v[128:131], s[4:5] offset:256
	s_add_u32 s4, s4, 0x58000
	s_addc_u32 s5, s5, 0
	s_nop 1
	v_mul_f32_e32 v132, s30, v28
	v_mul_f32_e32 v136, s30, v29
	v_mul_f32_e32 v133, s30, v30
	v_mul_f32_e32 v137, s30, v31
	v_mul_f32_e32 v134, s30, v24
	v_mul_f32_e32 v138, s30, v25
	v_mul_f32_e32 v135, s30, v26
	v_mul_f32_e32 v139, s30, v27
	v_cvt_pk_bf16_f32 v128, v132, v136
	v_cvt_pk_bf16_f32 v129, v133, v137
	v_cvt_pk_bf16_f32 v130, v134, v138
	v_cvt_pk_bf16_f32 v131, v135, v139
	global_store_dwordx4 v168, v[128:131], s[4:5]
	s_nop 1
	v_mul_f32_e32 v132, s30, v20
	v_mul_f32_e32 v136, s30, v21
	v_mul_f32_e32 v133, s30, v22
	v_mul_f32_e32 v137, s30, v23
	v_mul_f32_e32 v134, s30, v16
	v_mul_f32_e32 v138, s30, v17
	v_mul_f32_e32 v135, s30, v18
	v_mul_f32_e32 v139, s30, v19
	v_cvt_pk_bf16_f32 v128, v132, v136
	v_cvt_pk_bf16_f32 v129, v133, v137
	v_cvt_pk_bf16_f32 v130, v134, v138
	v_cvt_pk_bf16_f32 v131, v135, v139
	global_store_dwordx4 v168, v[128:131], s[4:5] offset:256
	s_add_u32 s4, s4, 0x58000
	s_addc_u32 s5, s5, 0
	s_nop 1
	v_mul_f32_e32 v132, s30, v12
	v_mul_f32_e32 v136, s30, v13
	v_mul_f32_e32 v133, s30, v14
	v_mul_f32_e32 v137, s30, v15
	v_mul_f32_e32 v134, s30, v8
	v_mul_f32_e32 v138, s30, v9
	v_mul_f32_e32 v135, s30, v10
	v_mul_f32_e32 v139, s30, v11
	v_cvt_pk_bf16_f32 v128, v132, v136
	v_cvt_pk_bf16_f32 v129, v133, v137
	v_cvt_pk_bf16_f32 v130, v134, v138
	v_cvt_pk_bf16_f32 v131, v135, v139
	global_store_dwordx4 v168, v[128:131], s[4:5]
	s_nop 1
	v_mul_f32_e32 v132, s30, v4
	v_mul_f32_e32 v136, s30, v5
	v_mul_f32_e32 v133, s30, v6
	v_mul_f32_e32 v137, s30, v7
	v_mul_f32_e32 v134, s30, v0
	v_mul_f32_e32 v138, s30, v1
	v_mul_f32_e32 v135, s30, v2
	v_mul_f32_e32 v139, s30, v3
	v_cvt_pk_bf16_f32 v128, v132, v136
	v_cvt_pk_bf16_f32 v129, v133, v137
	v_cvt_pk_bf16_f32 v130, v134, v138
	v_cvt_pk_bf16_f32 v131, v135, v139
	global_store_dwordx4 v168, v[128:131], s[4:5] offset:256
.Lepi4_done:
.LBB0_544:
	s_mov_b64 s[4:5], 0
.LBB0_545:
	s_andn2_b64 vcc, exec, s[4:5]
	s_cbranch_vccnz .LBB0_547
	s_lshl_b32 s4, s90, 8
	s_add_i32 s4, s4, s57
	v_lshl_add_u32 v132, v185, 3, s59
	v_add_u32_e32 v138, s4, v184
	v_mov_b64_e32 v[134:135], s[0:1]
	v_ashrrev_i32_e32 v133, 31, v132
	v_mad_i64_i32 v[136:137], s[4:5], v138, s28, v[134:135]
	s_lshl_b32 s20, s82, 9
	v_lshl_add_u64 v[136:137], v[136:137], 0, s[20:21]
	v_lshlrev_b64 v[132:133], 1, v[132:133]
	v_cvt_pk_bf16_f32 v128, v124, v125
	v_cvt_pk_bf16_f32 v129, v126, v127
	v_cvt_pk_bf16_f32 v130, v120, v121
	v_cvt_pk_bf16_f32 v131, v122, v123
	v_lshl_add_u64 v[136:137], v[136:137], 0, v[132:133]
	global_store_dwordx4 v[136:137], v[128:131], off
	s_nop 1
	v_cvt_pk_bf16_f32 v128, v116, v117
	v_cvt_pk_bf16_f32 v129, v118, v119
	v_cvt_pk_bf16_f32 v130, v112, v113
	v_cvt_pk_bf16_f32 v131, v114, v115
	global_store_dwordx4 v[136:137], v[128:131], off offset:256
	v_add_u32_e32 v136, 16, v138
	v_mad_i64_i32 v[136:137], s[4:5], v136, s28, v[134:135]
	v_lshl_add_u64 v[136:137], v[136:137], 0, s[20:21]
	v_cvt_pk_bf16_f32 v128, v108, v109
	v_cvt_pk_bf16_f32 v129, v110, v111
	v_cvt_pk_bf16_f32 v130, v104, v105
	v_cvt_pk_bf16_f32 v131, v106, v107
	v_lshl_add_u64 v[136:137], v[136:137], 0, v[132:133]
	global_store_dwordx4 v[136:137], v[128:131], off
	s_nop 1
	v_cvt_pk_bf16_f32 v128, v100, v101
	v_cvt_pk_bf16_f32 v129, v102, v103
	v_cvt_pk_bf16_f32 v130, v96, v97
	v_cvt_pk_bf16_f32 v131, v98, v99
	global_store_dwordx4 v[136:137], v[128:131], off offset:256
	v_add_u32_e32 v136, 32, v138
	v_mad_i64_i32 v[136:137], s[4:5], v136, s28, v[134:135]
	v_lshl_add_u64 v[136:137], v[136:137], 0, s[20:21]
	v_cvt_pk_bf16_f32 v128, v92, v93
	v_cvt_pk_bf16_f32 v129, v94, v95
	v_cvt_pk_bf16_f32 v130, v88, v89
	v_cvt_pk_bf16_f32 v131, v90, v91
	v_lshl_add_u64 v[136:137], v[136:137], 0, v[132:133]
	global_store_dwordx4 v[136:137], v[128:131], off
	s_nop 1
	v_cvt_pk_bf16_f32 v128, v84, v85
	v_cvt_pk_bf16_f32 v129, v86, v87
	v_cvt_pk_bf16_f32 v130, v80, v81
	v_cvt_pk_bf16_f32 v131, v82, v83
	global_store_dwordx4 v[136:137], v[128:131], off offset:256
	v_add_u32_e32 v136, 48, v138
	v_mad_i64_i32 v[136:137], s[4:5], v136, s28, v[134:135]
	v_lshl_add_u64 v[136:137], v[136:137], 0, s[20:21]
	v_cvt_pk_bf16_f32 v128, v76, v77
	v_cvt_pk_bf16_f32 v129, v78, v79
	v_cvt_pk_bf16_f32 v130, v72, v73
	v_cvt_pk_bf16_f32 v131, v74, v75
	v_lshl_add_u64 v[136:137], v[136:137], 0, v[132:133]
	global_store_dwordx4 v[136:137], v[128:131], off
	s_nop 1
	v_cvt_pk_bf16_f32 v128, v68, v69
	v_cvt_pk_bf16_f32 v129, v70, v71
	v_cvt_pk_bf16_f32 v130, v64, v65
	v_cvt_pk_bf16_f32 v131, v66, v67
	global_store_dwordx4 v[136:137], v[128:131], off offset:256
	v_add_u32_e32 v136, 0x80, v138
	v_mad_i64_i32 v[136:137], s[4:5], v136, s28, v[134:135]
	v_lshl_add_u64 v[136:137], v[136:137], 0, s[20:21]
	v_cvt_pk_bf16_f32 v128, v60, v61
	v_cvt_pk_bf16_f32 v129, v62, v63
	v_cvt_pk_bf16_f32 v130, v56, v57
	v_cvt_pk_bf16_f32 v131, v58, v59
	v_lshl_add_u64 v[136:137], v[136:137], 0, v[132:133]
	global_store_dwordx4 v[136:137], v[128:131], off
	s_nop 1
	v_cvt_pk_bf16_f32 v128, v52, v53
	v_cvt_pk_bf16_f32 v129, v54, v55
	v_cvt_pk_bf16_f32 v130, v48, v49
	v_cvt_pk_bf16_f32 v131, v50, v51
	global_store_dwordx4 v[136:137], v[128:131], off offset:256
	v_add_u32_e32 v136, 0x90, v138
	v_mad_i64_i32 v[136:137], s[4:5], v136, s28, v[134:135]
	v_lshl_add_u64 v[136:137], v[136:137], 0, s[20:21]
	v_cvt_pk_bf16_f32 v128, v44, v45
	v_cvt_pk_bf16_f32 v129, v46, v47
	v_cvt_pk_bf16_f32 v130, v40, v41
	v_cvt_pk_bf16_f32 v131, v42, v43
	v_lshl_add_u64 v[136:137], v[136:137], 0, v[132:133]
	global_store_dwordx4 v[136:137], v[128:131], off
	s_nop 1
	v_cvt_pk_bf16_f32 v128, v36, v37
	v_cvt_pk_bf16_f32 v129, v38, v39
	v_cvt_pk_bf16_f32 v130, v32, v33
	v_cvt_pk_bf16_f32 v131, v34, v35
	global_store_dwordx4 v[136:137], v[128:131], off offset:256
	v_add_u32_e32 v136, 0xa0, v138
	v_mad_i64_i32 v[136:137], s[4:5], v136, s28, v[134:135]
	v_lshl_add_u64 v[136:137], v[136:137], 0, s[20:21]
	v_cvt_pk_bf16_f32 v128, v28, v29
	v_cvt_pk_bf16_f32 v129, v30, v31
	v_cvt_pk_bf16_f32 v130, v24, v25
	v_cvt_pk_bf16_f32 v131, v26, v27
	v_lshl_add_u64 v[136:137], v[136:137], 0, v[132:133]
	global_store_dwordx4 v[136:137], v[128:131], off
	s_nop 1
	v_cvt_pk_bf16_f32 v128, v20, v21
	v_cvt_pk_bf16_f32 v129, v22, v23
	v_cvt_pk_bf16_f32 v130, v16, v17
	v_cvt_pk_bf16_f32 v131, v18, v19
	global_store_dwordx4 v[136:137], v[128:131], off offset:256
	v_add_u32_e32 v136, 0xb0, v138
	v_mad_i64_i32 v[134:135], s[4:5], v136, s28, v[134:135]
	v_lshl_add_u64 v[134:135], v[134:135], 0, s[20:21]
	v_cvt_pk_bf16_f32 v128, v12, v13
	v_cvt_pk_bf16_f32 v129, v14, v15
	v_cvt_pk_bf16_f32 v130, v8, v9
	v_cvt_pk_bf16_f32 v131, v10, v11
	v_lshl_add_u64 v[132:133], v[134:135], 0, v[132:133]
	global_store_dwordx4 v[132:133], v[128:131], off
	s_nop 1
	v_cvt_pk_bf16_f32 v128, v4, v5
	v_cvt_pk_bf16_f32 v129, v6, v7
	v_cvt_pk_bf16_f32 v130, v0, v1
	v_cvt_pk_bf16_f32 v131, v2, v3
	global_store_dwordx4 v[132:133], v[128:131], off offset:256
